# v22 + sc1 (write-through) on the first 10 of FF1's 16 bf16 U stores per unit
# speedup vs baseline: 1.0084x; 1.0084x over previous
.LBB0_215:
	v_mov_b32_e32 v0, v144
	v_mov_b32_e32 v142, v145
	s_lshl_b32 s50, s50, 8
	s_or_b32 s50, s50, s62
	s_ashr_i32 s55, s54, 31
	v_add_u32_e32 v148, s61, v0
	v_lshl_add_u32 v142, v142, 3, s50
	s_lshl_b64 s[50:51], s[54:55], 21
	v_readlane_b32 s54, v236, 59
	s_add_u32 s54, s54, s50
	v_readlane_b32 s50, v236, 56
	v_and_b32_e32 v149, 0xff, v148
	s_addc_u32 s55, s50, s51
	v_lshlrev_b32_e32 v0, 13, v149
	s_add_i32 s50, 0, 0x20400
	v_lshl_add_u64 v[150:151], s[54:55], 0, v[0:1]
	v_lshl_add_u32 v0, v149, 2, s50
	ds_read_b32 v0, v0
	v_ashrrev_i32_e32 v143, 31, v142
	v_lshlrev_b64 v[142:143], 1, v[142:143]
	v_lshl_add_u64 v[150:151], v[150:151], 0, v[142:143]
	s_movk_i32 s51, 0x80
	s_waitcnt lgkmcnt(0)
	v_pk_mul_f32 v[124:125], v[124:125], v[0:1] op_sel_hi:[1,0]
	v_pk_mul_f32 v[122:123], v[122:123], v[0:1] op_sel_hi:[1,0]
	v_pk_mul_f32 v[128:129], v[128:129], v[0:1] op_sel_hi:[1,0]
	v_pk_mul_f32 v[126:127], v[126:127], v[0:1] op_sel_hi:[1,0]
	v_max_f32_e32 v122, 0, v122
	v_max_f32_e32 v126, 0, v126
	v_max_f32_e32 v123, 0, v123
	v_max_f32_e32 v127, 0, v127
	v_max_f32_e32 v124, 0, v124
	v_max_f32_e32 v128, 0, v128
	v_max_f32_e32 v125, 0, v125
	v_max_f32_e32 v129, 0, v129
	v_pk_mul_f32 v[122:123], v[122:123], v[122:123]
	v_pk_mul_f32 v[126:127], v[126:127], v[126:127]
	v_pk_mul_f32 v[124:125], v[124:125], v[124:125]
	v_pk_mul_f32 v[128:129], v[128:129], v[128:129]
	v_pk_mul_f32 v[114:115], v[114:115], v[0:1] op_sel_hi:[1,0]
	v_cvt_pk_bf16_f32 v122, v122, v123
	v_cvt_pk_bf16_f32 v123, v124, v125
	v_cvt_pk_bf16_f32 v124, v126, v127
	v_cvt_pk_bf16_f32 v125, v128, v129
	v_pk_mul_f32 v[120:121], v[120:121], v[0:1] op_sel_hi:[1,0]
	v_pk_mul_f32 v[118:119], v[118:119], v[0:1] op_sel_hi:[1,0]
	v_pk_mul_f32 v[116:117], v[116:117], v[0:1] op_sel_hi:[1,0]
	v_max_f32_e32 v114, 0, v114
	v_max_f32_e32 v115, 0, v115
	global_store_dwordx4 v[150:151], v[122:125], off sc1
	v_max_f32_e32 v118, 0, v118
	v_max_f32_e32 v119, 0, v119
	v_pk_mul_f32 v[122:123], v[114:115], v[114:115]
	v_max_f32_e32 v114, 0, v120
	v_max_f32_e32 v116, 0, v116
	v_max_f32_e32 v115, 0, v121
	v_max_f32_e32 v117, 0, v117
	v_pk_mul_f32 v[118:119], v[118:119], v[118:119]
	v_pk_mul_f32 v[120:121], v[114:115], v[114:115]
	v_pk_mul_f32 v[124:125], v[116:117], v[116:117]
	v_cvt_pk_bf16_f32 v114, v118, v119
	v_cvt_pk_bf16_f32 v115, v120, v121
	v_cvt_pk_bf16_f32 v116, v122, v123
	v_cvt_pk_bf16_f32 v117, v124, v125
	v_add_u32_e32 v0, 16, v148
	global_store_dwordx4 v[150:151], v[114:117], off offset:256 sc1
	s_andn2_b64 vcc, exec, s[48:49]
	s_nop 0
	v_and_b32_e32 v116, 0xff, v0
	v_lshlrev_b32_e32 v0, 13, v116
	v_lshl_add_u64 v[114:115], s[54:55], 0, v[0:1]
	v_lshl_add_u32 v0, v116, 2, s50
	ds_read_b32 v0, v0
	v_lshl_add_u64 v[114:115], v[114:115], 0, v[142:143]
	s_waitcnt lgkmcnt(0)
	v_pk_mul_f32 v[106:107], v[106:107], v[0:1] op_sel_hi:[1,0]
	v_pk_mul_f32 v[112:113], v[112:113], v[0:1] op_sel_hi:[1,0]
	v_pk_mul_f32 v[110:111], v[110:111], v[0:1] op_sel_hi:[1,0]
	v_pk_mul_f32 v[108:109], v[108:109], v[0:1] op_sel_hi:[1,0]
	v_max_f32_e32 v106, 0, v106
	v_max_f32_e32 v107, 0, v107
	v_max_f32_e32 v110, 0, v110
	v_max_f32_e32 v111, 0, v111
	v_pk_mul_f32 v[116:117], v[106:107], v[106:107]
	v_max_f32_e32 v106, 0, v112
	v_max_f32_e32 v108, 0, v108
	v_max_f32_e32 v107, 0, v113
	v_max_f32_e32 v109, 0, v109
	v_pk_mul_f32 v[110:111], v[110:111], v[110:111]
	v_pk_mul_f32 v[112:113], v[106:107], v[106:107]
	v_pk_mul_f32 v[118:119], v[108:109], v[108:109]
	v_pk_mul_f32 v[98:99], v[98:99], v[0:1] op_sel_hi:[1,0]
	v_cvt_pk_bf16_f32 v106, v110, v111
	v_cvt_pk_bf16_f32 v107, v112, v113
	v_cvt_pk_bf16_f32 v108, v116, v117
	v_cvt_pk_bf16_f32 v109, v118, v119
	v_pk_mul_f32 v[104:105], v[104:105], v[0:1] op_sel_hi:[1,0]
	v_pk_mul_f32 v[102:103], v[102:103], v[0:1] op_sel_hi:[1,0]
	v_pk_mul_f32 v[100:101], v[100:101], v[0:1] op_sel_hi:[1,0]
	v_max_f32_e32 v98, 0, v98
	v_max_f32_e32 v99, 0, v99
	global_store_dwordx4 v[114:115], v[106:109], off sc1
	v_max_f32_e32 v102, 0, v102
	v_max_f32_e32 v103, 0, v103
	v_pk_mul_f32 v[106:107], v[98:99], v[98:99]
	v_max_f32_e32 v98, 0, v104
	v_max_f32_e32 v100, 0, v100
	v_max_f32_e32 v99, 0, v105
	v_max_f32_e32 v101, 0, v101
	v_pk_mul_f32 v[102:103], v[102:103], v[102:103]
	v_pk_mul_f32 v[104:105], v[98:99], v[98:99]
	v_pk_mul_f32 v[108:109], v[100:101], v[100:101]
	v_cvt_pk_bf16_f32 v98, v102, v103
	v_cvt_pk_bf16_f32 v99, v104, v105
	v_cvt_pk_bf16_f32 v100, v106, v107
	v_cvt_pk_bf16_f32 v101, v108, v109
	v_add_u32_e32 v0, 32, v148
	global_store_dwordx4 v[114:115], v[98:101], off offset:256 sc1
	s_nop 1
	v_and_b32_e32 v100, 0xff, v0
	v_lshlrev_b32_e32 v0, 13, v100
	v_lshl_add_u64 v[98:99], s[54:55], 0, v[0:1]
	v_lshl_add_u32 v0, v100, 2, s50
	ds_read_b32 v0, v0
	v_lshl_add_u64 v[98:99], v[98:99], 0, v[142:143]
	s_waitcnt lgkmcnt(0)
	v_pk_mul_f32 v[90:91], v[90:91], v[0:1] op_sel_hi:[1,0]
	v_pk_mul_f32 v[96:97], v[96:97], v[0:1] op_sel_hi:[1,0]
	v_pk_mul_f32 v[94:95], v[94:95], v[0:1] op_sel_hi:[1,0]
	v_pk_mul_f32 v[92:93], v[92:93], v[0:1] op_sel_hi:[1,0]
	v_max_f32_e32 v90, 0, v90
	v_max_f32_e32 v91, 0, v91
	v_max_f32_e32 v94, 0, v94
	v_max_f32_e32 v95, 0, v95
	v_pk_mul_f32 v[100:101], v[90:91], v[90:91]
	v_max_f32_e32 v90, 0, v96
	v_max_f32_e32 v92, 0, v92
	v_max_f32_e32 v91, 0, v97
	v_max_f32_e32 v93, 0, v93
	v_pk_mul_f32 v[94:95], v[94:95], v[94:95]
	v_pk_mul_f32 v[96:97], v[90:91], v[90:91]
	v_pk_mul_f32 v[102:103], v[92:93], v[92:93]
	v_pk_mul_f32 v[82:83], v[82:83], v[0:1] op_sel_hi:[1,0]
	v_cvt_pk_bf16_f32 v90, v94, v95
	v_cvt_pk_bf16_f32 v91, v96, v97
	v_cvt_pk_bf16_f32 v92, v100, v101
	v_cvt_pk_bf16_f32 v93, v102, v103
	v_pk_mul_f32 v[88:89], v[88:89], v[0:1] op_sel_hi:[1,0]
	v_pk_mul_f32 v[86:87], v[86:87], v[0:1] op_sel_hi:[1,0]
	v_pk_mul_f32 v[84:85], v[84:85], v[0:1] op_sel_hi:[1,0]
	v_max_f32_e32 v82, 0, v82
	v_max_f32_e32 v83, 0, v83
	global_store_dwordx4 v[98:99], v[90:93], off sc1
	v_max_f32_e32 v86, 0, v86
	v_max_f32_e32 v87, 0, v87
	v_pk_mul_f32 v[90:91], v[82:83], v[82:83]
	v_max_f32_e32 v82, 0, v88
	v_max_f32_e32 v84, 0, v84
	v_max_f32_e32 v83, 0, v89
	v_max_f32_e32 v85, 0, v85
	v_pk_mul_f32 v[86:87], v[86:87], v[86:87]
	v_pk_mul_f32 v[88:89], v[82:83], v[82:83]
	v_pk_mul_f32 v[92:93], v[84:85], v[84:85]
	v_cvt_pk_bf16_f32 v82, v86, v87
	v_cvt_pk_bf16_f32 v83, v88, v89
	v_cvt_pk_bf16_f32 v84, v90, v91
	v_cvt_pk_bf16_f32 v85, v92, v93
	v_add_u32_e32 v0, 48, v148
	global_store_dwordx4 v[98:99], v[82:85], off offset:256 sc1
	s_nop 1
	v_and_b32_e32 v84, 0xff, v0
	v_lshlrev_b32_e32 v0, 13, v84
	v_lshl_add_u64 v[82:83], s[54:55], 0, v[0:1]
	v_lshl_add_u32 v0, v84, 2, s50
	ds_read_b32 v0, v0
	v_lshl_add_u64 v[82:83], v[82:83], 0, v[142:143]
	s_waitcnt lgkmcnt(0)
	v_pk_mul_f32 v[74:75], v[74:75], v[0:1] op_sel_hi:[1,0]
	v_pk_mul_f32 v[80:81], v[80:81], v[0:1] op_sel_hi:[1,0]
	v_pk_mul_f32 v[78:79], v[78:79], v[0:1] op_sel_hi:[1,0]
	v_pk_mul_f32 v[76:77], v[76:77], v[0:1] op_sel_hi:[1,0]
	v_max_f32_e32 v74, 0, v74
	v_max_f32_e32 v75, 0, v75
	v_max_f32_e32 v78, 0, v78
	v_max_f32_e32 v79, 0, v79
	v_pk_mul_f32 v[84:85], v[74:75], v[74:75]
	v_max_f32_e32 v74, 0, v80
	v_max_f32_e32 v76, 0, v76
	v_max_f32_e32 v75, 0, v81
	v_max_f32_e32 v77, 0, v77
	v_pk_mul_f32 v[78:79], v[78:79], v[78:79]
	v_pk_mul_f32 v[80:81], v[74:75], v[74:75]
	v_pk_mul_f32 v[86:87], v[76:77], v[76:77]
	v_pk_mul_f32 v[66:67], v[66:67], v[0:1] op_sel_hi:[1,0]
	v_cvt_pk_bf16_f32 v74, v78, v79
	v_cvt_pk_bf16_f32 v75, v80, v81
	v_cvt_pk_bf16_f32 v76, v84, v85
	v_cvt_pk_bf16_f32 v77, v86, v87
	v_pk_mul_f32 v[72:73], v[72:73], v[0:1] op_sel_hi:[1,0]
	v_pk_mul_f32 v[70:71], v[70:71], v[0:1] op_sel_hi:[1,0]
	v_pk_mul_f32 v[68:69], v[68:69], v[0:1] op_sel_hi:[1,0]
	v_max_f32_e32 v66, 0, v66
	v_max_f32_e32 v67, 0, v67
	global_store_dwordx4 v[82:83], v[74:77], off sc1
	v_max_f32_e32 v70, 0, v70
	v_max_f32_e32 v71, 0, v71
	v_pk_mul_f32 v[74:75], v[66:67], v[66:67]
	v_max_f32_e32 v66, 0, v72
	v_max_f32_e32 v68, 0, v68
	v_max_f32_e32 v67, 0, v73
	v_max_f32_e32 v69, 0, v69
	v_pk_mul_f32 v[70:71], v[70:71], v[70:71]
	v_pk_mul_f32 v[72:73], v[66:67], v[66:67]
	v_pk_mul_f32 v[76:77], v[68:69], v[68:69]
	v_cvt_pk_bf16_f32 v66, v70, v71
	v_cvt_pk_bf16_f32 v67, v72, v73
	v_cvt_pk_bf16_f32 v68, v74, v75
	v_cvt_pk_bf16_f32 v69, v76, v77
	global_store_dwordx4 v[82:83], v[66:69], off offset:256 sc1
	s_nop 1
	v_bitop3_b32 v68, v148, s51, v195 bitop3:0x6c
	v_lshlrev_b32_e32 v0, 13, v68
	v_lshl_add_u64 v[66:67], s[54:55], 0, v[0:1]
	v_lshl_add_u32 v0, v68, 2, s50
	ds_read_b32 v0, v0
	v_lshl_add_u64 v[66:67], v[66:67], 0, v[142:143]
	s_waitcnt lgkmcnt(0)
	v_pk_mul_f32 v[58:59], v[58:59], v[0:1] op_sel_hi:[1,0]
	v_pk_mul_f32 v[64:65], v[64:65], v[0:1] op_sel_hi:[1,0]
	v_pk_mul_f32 v[62:63], v[62:63], v[0:1] op_sel_hi:[1,0]
	v_pk_mul_f32 v[60:61], v[60:61], v[0:1] op_sel_hi:[1,0]
	v_max_f32_e32 v58, 0, v58
	v_max_f32_e32 v59, 0, v59
	v_max_f32_e32 v62, 0, v62
	v_max_f32_e32 v63, 0, v63
	v_pk_mul_f32 v[68:69], v[58:59], v[58:59]
	v_max_f32_e32 v58, 0, v64
	v_max_f32_e32 v60, 0, v60
	v_max_f32_e32 v59, 0, v65
	v_max_f32_e32 v61, 0, v61
	v_pk_mul_f32 v[62:63], v[62:63], v[62:63]
	v_pk_mul_f32 v[64:65], v[58:59], v[58:59]
	v_pk_mul_f32 v[70:71], v[60:61], v[60:61]
	v_pk_mul_f32 v[50:51], v[50:51], v[0:1] op_sel_hi:[1,0]
	v_cvt_pk_bf16_f32 v58, v62, v63
	v_cvt_pk_bf16_f32 v59, v64, v65
	v_cvt_pk_bf16_f32 v60, v68, v69
	v_cvt_pk_bf16_f32 v61, v70, v71
	v_pk_mul_f32 v[56:57], v[56:57], v[0:1] op_sel_hi:[1,0]
	v_pk_mul_f32 v[54:55], v[54:55], v[0:1] op_sel_hi:[1,0]
	v_pk_mul_f32 v[52:53], v[52:53], v[0:1] op_sel_hi:[1,0]
	v_max_f32_e32 v50, 0, v50
	v_max_f32_e32 v51, 0, v51
	global_store_dwordx4 v[66:67], v[58:61], off sc1
	v_max_f32_e32 v54, 0, v54
	v_max_f32_e32 v55, 0, v55
	v_pk_mul_f32 v[58:59], v[50:51], v[50:51]
	v_max_f32_e32 v50, 0, v56
	v_max_f32_e32 v52, 0, v52
	v_max_f32_e32 v51, 0, v57
	v_max_f32_e32 v53, 0, v53
	v_pk_mul_f32 v[54:55], v[54:55], v[54:55]
	v_pk_mul_f32 v[56:57], v[50:51], v[50:51]
	v_pk_mul_f32 v[60:61], v[52:53], v[52:53]
	v_cvt_pk_bf16_f32 v50, v54, v55
	v_cvt_pk_bf16_f32 v51, v56, v57
	v_cvt_pk_bf16_f32 v52, v58, v59
	v_cvt_pk_bf16_f32 v53, v60, v61
	v_add_u32_e32 v0, 0x90, v148
	global_store_dwordx4 v[66:67], v[50:53], off offset:256 sc1
	s_nop 1
	v_and_b32_e32 v52, 0xff, v0
	v_lshlrev_b32_e32 v0, 13, v52
	v_lshl_add_u64 v[50:51], s[54:55], 0, v[0:1]
	v_lshl_add_u32 v0, v52, 2, s50
	ds_read_b32 v0, v0
	v_lshl_add_u64 v[50:51], v[50:51], 0, v[142:143]
	s_waitcnt lgkmcnt(0)
	v_pk_mul_f32 v[42:43], v[42:43], v[0:1] op_sel_hi:[1,0]
	v_pk_mul_f32 v[48:49], v[48:49], v[0:1] op_sel_hi:[1,0]
	v_pk_mul_f32 v[46:47], v[46:47], v[0:1] op_sel_hi:[1,0]
	v_pk_mul_f32 v[44:45], v[44:45], v[0:1] op_sel_hi:[1,0]
	v_max_f32_e32 v42, 0, v42
	v_max_f32_e32 v43, 0, v43
	v_max_f32_e32 v46, 0, v46
	v_max_f32_e32 v47, 0, v47
	v_pk_mul_f32 v[52:53], v[42:43], v[42:43]
	v_max_f32_e32 v42, 0, v48
	v_max_f32_e32 v44, 0, v44
	v_max_f32_e32 v43, 0, v49
	v_max_f32_e32 v45, 0, v45
	v_pk_mul_f32 v[46:47], v[46:47], v[46:47]
	v_pk_mul_f32 v[48:49], v[42:43], v[42:43]
	v_pk_mul_f32 v[54:55], v[44:45], v[44:45]
	v_pk_mul_f32 v[34:35], v[34:35], v[0:1] op_sel_hi:[1,0]
	v_cvt_pk_bf16_f32 v42, v46, v47
	v_cvt_pk_bf16_f32 v43, v48, v49
	v_cvt_pk_bf16_f32 v44, v52, v53
	v_cvt_pk_bf16_f32 v45, v54, v55
	v_pk_mul_f32 v[40:41], v[40:41], v[0:1] op_sel_hi:[1,0]
	v_pk_mul_f32 v[38:39], v[38:39], v[0:1] op_sel_hi:[1,0]
	v_pk_mul_f32 v[36:37], v[36:37], v[0:1] op_sel_hi:[1,0]
	v_max_f32_e32 v34, 0, v34
	v_max_f32_e32 v35, 0, v35
	global_store_dwordx4 v[50:51], v[42:45], off
	v_max_f32_e32 v38, 0, v38
	v_max_f32_e32 v39, 0, v39
	v_pk_mul_f32 v[42:43], v[34:35], v[34:35]
	v_max_f32_e32 v34, 0, v40
	v_max_f32_e32 v36, 0, v36
	v_max_f32_e32 v35, 0, v41
	v_max_f32_e32 v37, 0, v37
	v_pk_mul_f32 v[38:39], v[38:39], v[38:39]
	v_pk_mul_f32 v[40:41], v[34:35], v[34:35]
	v_pk_mul_f32 v[44:45], v[36:37], v[36:37]
	v_cvt_pk_bf16_f32 v34, v38, v39
	v_cvt_pk_bf16_f32 v35, v40, v41
	v_cvt_pk_bf16_f32 v36, v42, v43
	v_cvt_pk_bf16_f32 v37, v44, v45
	v_add_u32_e32 v0, 0xa0, v148
	global_store_dwordx4 v[50:51], v[34:37], off offset:256
	s_nop 1
	v_and_b32_e32 v36, 0xff, v0
	v_lshlrev_b32_e32 v0, 13, v36
	v_lshl_add_u64 v[34:35], s[54:55], 0, v[0:1]
	v_lshl_add_u32 v0, v36, 2, s50
	ds_read_b32 v0, v0
	v_lshl_add_u64 v[34:35], v[34:35], 0, v[142:143]
	s_waitcnt lgkmcnt(0)
	v_pk_mul_f32 v[26:27], v[26:27], v[0:1] op_sel_hi:[1,0]
	v_pk_mul_f32 v[32:33], v[32:33], v[0:1] op_sel_hi:[1,0]
	v_pk_mul_f32 v[30:31], v[30:31], v[0:1] op_sel_hi:[1,0]
	v_pk_mul_f32 v[28:29], v[28:29], v[0:1] op_sel_hi:[1,0]
	v_max_f32_e32 v26, 0, v26
	v_max_f32_e32 v27, 0, v27
	v_max_f32_e32 v30, 0, v30
	v_max_f32_e32 v31, 0, v31
	v_pk_mul_f32 v[36:37], v[26:27], v[26:27]
	v_max_f32_e32 v26, 0, v32
	v_max_f32_e32 v28, 0, v28
	v_max_f32_e32 v27, 0, v33
	v_max_f32_e32 v29, 0, v29
	v_pk_mul_f32 v[30:31], v[30:31], v[30:31]
	v_pk_mul_f32 v[32:33], v[26:27], v[26:27]
	v_pk_mul_f32 v[38:39], v[28:29], v[28:29]
	v_pk_mul_f32 v[18:19], v[18:19], v[0:1] op_sel_hi:[1,0]
	v_cvt_pk_bf16_f32 v26, v30, v31
	v_cvt_pk_bf16_f32 v27, v32, v33
	v_cvt_pk_bf16_f32 v28, v36, v37
	v_cvt_pk_bf16_f32 v29, v38, v39
	v_pk_mul_f32 v[24:25], v[24:25], v[0:1] op_sel_hi:[1,0]
	v_pk_mul_f32 v[22:23], v[22:23], v[0:1] op_sel_hi:[1,0]
	v_pk_mul_f32 v[20:21], v[20:21], v[0:1] op_sel_hi:[1,0]
	v_max_f32_e32 v18, 0, v18
	v_max_f32_e32 v19, 0, v19
	global_store_dwordx4 v[34:35], v[26:29], off
	v_max_f32_e32 v22, 0, v22
	v_max_f32_e32 v23, 0, v23
	v_pk_mul_f32 v[26:27], v[18:19], v[18:19]
	v_max_f32_e32 v18, 0, v24
	v_max_f32_e32 v20, 0, v20
	v_max_f32_e32 v19, 0, v25
	v_max_f32_e32 v21, 0, v21
	v_pk_mul_f32 v[22:23], v[22:23], v[22:23]
	v_pk_mul_f32 v[24:25], v[18:19], v[18:19]
	v_pk_mul_f32 v[28:29], v[20:21], v[20:21]
	v_cvt_pk_bf16_f32 v18, v22, v23
	v_cvt_pk_bf16_f32 v19, v24, v25
	v_cvt_pk_bf16_f32 v20, v26, v27
	v_cvt_pk_bf16_f32 v21, v28, v29
	v_add_u32_e32 v0, 0xb0, v148
	global_store_dwordx4 v[34:35], v[18:21], off offset:256
	s_nop 1
	v_and_b32_e32 v20, 0xff, v0
	v_lshlrev_b32_e32 v0, 13, v20
	v_lshl_add_u64 v[18:19], s[54:55], 0, v[0:1]
	v_lshl_add_u32 v0, v20, 2, s50
	ds_read_b32 v0, v0
	v_lshl_add_u64 v[18:19], v[18:19], 0, v[142:143]
	s_mov_b64 s[50:51], -1
	s_waitcnt lgkmcnt(0)
	v_pk_mul_f32 v[10:11], v[10:11], v[0:1] op_sel_hi:[1,0]
	v_pk_mul_f32 v[16:17], v[16:17], v[0:1] op_sel_hi:[1,0]
	v_pk_mul_f32 v[14:15], v[14:15], v[0:1] op_sel_hi:[1,0]
	v_pk_mul_f32 v[12:13], v[12:13], v[0:1] op_sel_hi:[1,0]
	v_max_f32_e32 v10, 0, v10
	v_max_f32_e32 v11, 0, v11
	v_max_f32_e32 v14, 0, v14
	v_max_f32_e32 v15, 0, v15
	v_pk_mul_f32 v[20:21], v[10:11], v[10:11]
	v_max_f32_e32 v10, 0, v16
	v_max_f32_e32 v12, 0, v12
	v_max_f32_e32 v11, 0, v17
	v_max_f32_e32 v13, 0, v13
	v_pk_mul_f32 v[14:15], v[14:15], v[14:15]
	v_pk_mul_f32 v[16:17], v[10:11], v[10:11]
	v_pk_mul_f32 v[22:23], v[12:13], v[12:13]
	v_pk_mul_f32 v[2:3], v[2:3], v[0:1] op_sel_hi:[1,0]
	v_cvt_pk_bf16_f32 v10, v14, v15
	v_cvt_pk_bf16_f32 v11, v16, v17
	v_cvt_pk_bf16_f32 v12, v20, v21
	v_cvt_pk_bf16_f32 v13, v22, v23
	v_pk_mul_f32 v[8:9], v[8:9], v[0:1] op_sel_hi:[1,0]
	v_pk_mul_f32 v[6:7], v[6:7], v[0:1] op_sel_hi:[1,0]
	v_pk_mul_f32 v[4:5], v[4:5], v[0:1] op_sel_hi:[1,0]
	v_max_f32_e32 v2, 0, v2
	v_max_f32_e32 v3, 0, v3
	global_store_dwordx4 v[18:19], v[10:13], off
	v_max_f32_e32 v6, 0, v6
	v_max_f32_e32 v7, 0, v7
	v_pk_mul_f32 v[10:11], v[2:3], v[2:3]
	v_max_f32_e32 v2, 0, v8
	v_max_f32_e32 v4, 0, v4
	v_max_f32_e32 v3, 0, v9
	v_max_f32_e32 v5, 0, v5
	v_pk_mul_f32 v[6:7], v[6:7], v[6:7]
	v_pk_mul_f32 v[8:9], v[2:3], v[2:3]
	v_pk_mul_f32 v[12:13], v[4:5], v[4:5]
	v_cvt_pk_bf16_f32 v2, v6, v7
	v_cvt_pk_bf16_f32 v3, v8, v9
	v_cvt_pk_bf16_f32 v4, v10, v11
	v_cvt_pk_bf16_f32 v5, v12, v13
	global_store_dwordx4 v[18:19], v[2:5], off offset:256
	s_cbranch_vccnz .LBB0_206
	s_andn2_b64 vcc, exec, s[40:41]
	s_cbranch_vccnz .LBB0_205
	s_barrier
	s_branch .LBB0_205
